# v18 + attention unit prologue requests K/V tiles 0..2 right behind the Q/rope loads instead of after the rope math
# baseline (speedup 1.0000x reference)
; __device__ __forceinline__ void load_q(bf16x8 (&qf)[6], const bf16_t* qn, const bf16_t* qr, const float* rp, int hi) {
; #pragma unroll
;     for (int d0 = 0; d0 < 4; ++d0) qf[d0] = *(const bf16x8*)(qn + d0 * 16 + hi * 8);
;     const u32x4 a = *(const u32x4*)(qr + hi * 8), b = *(const u32x4*)(qr + 16 + hi * 8);
;     const f32x4 c0 = *(const f32x4*)(rp + hi * 8), c1 = *(const f32x4*)(rp + hi * 8 + 4), s0 = *(const f32x4*)(rp + 16 + hi * 8), s1 = *(const f32x4*)(rp + 16 + hi * 8 + 4);
; __device__ __forceinline__ void prompt_unit(LAS unsigned char* lds, const Ptrs& P, int qloc0, int qglob0, int kloc0, int kglob0, int h, int qb) {
;     ...
;     { const int ql = qloc0 + 32 * wid + r32, pos = qb * 256 + 32 * wid + r32;
;       load_q(qf, P.Qn + (size_t)ql * 1024 + h * 64, P.Qr + (size_t)ql * 512 + h * 32, P.rope + pos * 32, hi); }
;     const bf16_t* kn_src = P.Kn + (size_t)(kloc0 + (tid >> 3)) * 1024 + h * 64 + (tid & 7) * 8;
;     const bf16_t* vt_src = P.Vt + (size_t)(h * 64 + (tid >> 3)) * VT_LD + kloc0 + (tid & 7) * 8;
;     const bf16_t* kr_src = P.KR + (size_t)(kglob0 + ((tid & 255) >> 2)) * 32 + (tid & 3) * 8;
;     const int k_w = (tid >> 3) * KP + (tid & 7) * 16, r_w = ((tid & 255) >> 2) * KP + 128 + (tid & 3) * 16;
;     const int v_w = KB + (tid >> 3) * VP + ((tid & 7) >> 1) * 32 + (tid & 1) * 8;
;     u32x4 kreg, vreg, rreg = (u32x4){0u, 0u, 0u, 0u};
;     kreg = *(const u32x4*)kn_src; vreg = *(const u32x4*)vt_src; if (tid < 256) rreg = *(const u32x4*)kr_src;
.LBB0_1143:
	v_mov_b32_e32 v16, v167
	s_and_b64 s[38:39], s[66:67], exec
	s_cselect_b32 s68, s3, s25
	v_readfirstlane_b32 s69, v16
	s_ashr_i32 s39, s69, 1
	s_lshl_b32 s27, s68, 8
	s_and_b32 s64, s39, 0xffffffe0
	v_mov_b32_e32 v0, s39
	s_movk_i32 s39, 0xffe0
	s_or_b32 s38, s27, s8
	v_bfi_b32 v143, s39, v0, v16
	v_add_u32_e32 v0, s38, v143
	v_and_b32_e32 v17, 31, v16
	s_add_i32 s64, s64, s27
	v_ashrrev_i32_e32 v1, 31, v0
	v_bfe_u32 v142, v16, 5, 1
	v_or_b32_e32 v4, s64, v17
	v_lshlrev_b64 v[2:3], 11, v[0:1]
	v_lshlrev_b64 v[0:1], 10, v[0:1]
	v_lshl_add_u64 v[2:3], s[16:17], 0, v[2:3]
	v_lshl_add_u64 v[0:1], s[22:23], 0, v[0:1]
	v_lshlrev_b32_e32 v4, 5, v4
	v_lshlrev_b32_e32 v64, 4, v142
	v_ashrrev_i32_e32 v5, 31, v4
	v_lshl_add_u64 v[2:3], v[2:3], 0, v[64:65]
	v_lshl_add_u64 v[0:1], v[0:1], 0, v[64:65]
	v_lshl_add_u64 v[4:5], v[4:5], 2, s[14:15]
	global_load_dwordx4 v[78:81], v[2:3], off
	global_load_dwordx4 v[74:77], v[2:3], off offset:32
	global_load_dwordx4 v[70:73], v[2:3], off offset:64
	s_waitcnt lgkmcnt(0)
	global_load_dwordx4 v[66:69], v[2:3], off offset:96
	global_load_dwordx4 v[8:11], v[0:1], off
	global_load_dwordx4 v[12:15], v[0:1], off offset:32
	v_lshlrev_b32_e32 v0, 5, v142
	v_mov_b32_e32 v1, v65
	v_lshl_add_u64 v[22:23], v[4:5], 0, v[0:1]
	global_load_dwordx4 v[0:3], v[22:23], off offset:16
	global_load_dwordx4 v[18:21], v[22:23], off
	global_load_dwordx4 v[4:7], v[22:23], off offset:80
	s_nop 0
	global_load_dwordx4 v[22:25], v[22:23], off offset:64
	v_ashrrev_i32_e32 v114, 3, v16
	v_add_u32_e32 v116, s8, v114
	v_ashrrev_i32_e32 v117, 31, v116
	v_and_b32_e32 v118, 7, v16
	v_lshlrev_b64 v[116:117], 11, v[116:117]
	v_lshlrev_b32_e32 v120, 4, v118
	v_add_u32_e32 v122, s26, v114
	v_mov_b64_e32 v[118:119], s[30:31]
	v_lshl_add_u64 v[116:117], s[28:29], 0, v[116:117]
	v_mov_b32_e32 v121, v65
	v_mad_i64_i32 v[118:119], s[38:39], v122, s77, v[118:119]
	v_lshl_add_u64 v[116:117], v[116:117], 0, v[120:121]
	v_lshl_add_u64 v[118:119], v[118:119], 0, v[120:121]
	v_add_co_u32_e32 v98, vcc, 0x20000, v116
	s_nop 1
	v_addc_co_u32_e32 v99, vcc, 0, v117, vcc
	v_add_co_u32_e32 v180, vcc, 0x40000, v116
	s_nop 1
	v_addc_co_u32_e32 v181, vcc, 0, v117, vcc
	v_lshl_add_u64 v[94:95], v[118:119], 0, s[44:45]
	v_lshl_add_u64 v[176:177], v[94:95], 0, s[44:45]
	global_load_dwordx4 v[106:109], v[116:117], off
	global_load_dwordx4 v[110:113], v[118:119], off
	s_movk_i32 s38, 0x100
	v_and_b32_e32 v123, 3, v16
	v_bfe_u32 v124, v16, 2, 6
	v_cmp_gt_i32_e64 s[38:39], s38, v16
	v_lshlrev_b32_e32 v120, 4, v123
	s_and_saveexec_b64 s[64:65], s[38:39]
	s_cbranch_execz .Latt_pro_kr_done
	v_or_b32_e32 v122, s24, v124
	v_ashrrev_i32_e32 v123, 31, v122
	v_lshlrev_b64 v[122:123], 6, v[122:123]
	v_lshl_add_u64 v[122:123], s[12:13], 0, v[122:123]
	v_lshl_add_u64 v[122:123], v[122:123], 0, v[120:121]
	global_load_dwordx4 v[102:105], v[122:123], off
	v_lshl_add_u64 v[122:123], v[122:123], 0, s[34:35]
	global_load_dwordx4 v[90:93], v[122:123], off
	v_lshl_add_u64 v[122:123], v[122:123], 0, s[34:35]
	global_load_dwordx4 v[172:175], v[122:123], off
; __device__ __forceinline__ float bflo(unsigned w) { return __uint_as_float(w << 16); }
; __device__ __forceinline__ float bfhi(unsigned w) { return __uint_as_float(w & 0xffff0000u); }
; #define LAS __attribute__((address_space(3)))
; __device__ __forceinline__ unsigned pk2(float lo, float hi) { return pg8::cvt_pk_bf16(lo, hi); }
; __device__ __forceinline__ float bflo(unsigned w) { return __uint_as_float(w << 16); }
; __device__ __forceinline__ float bfhi(unsigned w) { return __uint_as_float(w & 0xffff0000u); }
; __device__ __forceinline__ void load_q(bf16x8 (&qf)[6], const bf16_t* qn, const bf16_t* qr, const float* rp, int hi) {
;     ...
;     const float x1[8] = {bflo(a.x), bfhi(a.x), bflo(a.y), bfhi(a.y), bflo(a.z), bfhi(a.z), bflo(a.w), bfhi(a.w)};
;     const float x2[8] = {bflo(b.x), bfhi(b.x), bflo(b.y), bfhi(b.y), bflo(b.z), bfhi(b.z), bflo(b.w), bfhi(b.w)};
;     const float cs[8] = {c0[0], c0[1], c0[2], c0[3], c1[0], c1[1], c1[2], c1[3]}, sn[8] = {s0[0], s0[1], s0[2], s0[3], s1[0], s1[1], s1[2], s1[3]};
;     float o1[8], o2[8];
; #pragma unroll
;     for (int j = 0; j < 8; ++j) { o1[j] = x1[j] * cs[j] - x2[j] * sn[j]; o2[j] = x1[j] * sn[j] + x2[j] * cs[j]; }
;     u32x4 w1 = (u32x4){pk2(o1[0], o1[1]), pk2(o1[2], o1[3]), pk2(o1[4], o1[5]), pk2(o1[6], o1[7])}, w2 = (u32x4){pk2(o2[0], o2[1]), pk2(o2[2], o2[3]), pk2(o2[4], o2[5]), pk2(o2[6], o2[7])};
;     qf[4] = __builtin_bit_cast(bf16x8, w1); qf[5] = __builtin_bit_cast(bf16x8, w2);
; __device__ __forceinline__ void prompt_unit(LAS unsigned char* lds, const Ptrs& P, int qloc0, int qglob0, int kloc0, int kglob0, int h, int qb) {
;     ...
;     const int k_w = (tid >> 3) * KP + (tid & 7) * 16, r_w = ((tid & 255) >> 2) * KP + 128 + (tid & 3) * 16;
;     const int v_w = KB + (tid >> 3) * VP + ((tid & 7) >> 1) * 32 + (tid & 1) * 8;
;     u32x4 kreg, vreg, rreg = (u32x4){0u, 0u, 0u, 0u};
;     kreg = *(const u32x4*)kn_src; vreg = *(const u32x4*)vt_src; if (tid < 256) rreg = *(const u32x4*)kr_src;
;     *(LAS u32x4*)(lds + k_w) = kreg; if (tid < 256) *(LAS u32x4*)(lds + r_w) = rreg;
;     *(LAS u32x2*)(lds + v_w) = (u32x2){vreg.x, vreg.y}; *(LAS u32x2*)(lds + v_w + 16) = (u32x2){vreg.z, vreg.w};
.Latt_pro_kr_done:
	s_or_b64 exec, exec, s[64:65]
	global_load_dwordx4 v[98:101], v[98:99], off
	global_load_dwordx4 v[94:97], v[94:95], off
	global_load_dwordx4 v[180:183], v[180:181], off
	global_load_dwordx4 v[176:179], v[176:177], off
	s_waitcnt vmcnt(11)
	v_lshlrev_b32_e32 v27, 16, v8
	s_waitcnt vmcnt(10)
	v_lshlrev_b32_e32 v26, 16, v12
	s_waitcnt vmcnt(8)
	v_mov_b32_e32 v29, v18
	s_waitcnt vmcnt(6)
	v_mov_b32_e32 v28, v22
	v_pk_mul_f32 v[28:29], v[28:29], v[26:27]
	s_nop 0
	v_sub_f32_e32 v30, v29, v28
	v_mov_b32_e32 v28, v18
	v_mov_b32_e32 v29, v22
	v_pk_mul_f32 v[26:27], v[28:29], v[26:27]
	v_mov_b32_e32 v18, v23
	v_add_f32_e32 v31, v26, v27
	v_and_b32_e32 v27, 0xffff0000, v8
	v_and_b32_e32 v26, 0xffff0000, v12
	v_mov_b32_e32 v22, v19
	v_pk_mul_f32 v[28:29], v[18:19], v[26:27]
	v_pk_mul_f32 v[18:19], v[22:23], v[26:27]
	v_mov_b32_e32 v22, v24
	v_add_f32_e32 v26, v18, v19
	v_lshlrev_b32_e32 v19, 16, v9
	v_lshlrev_b32_e32 v18, 16, v13
	v_mov_b32_e32 v23, v20
	v_pk_mul_f32 v[22:23], v[22:23], v[18:19]
	v_and_b32_e32 v9, 0xffff0000, v9
	v_sub_f32_e32 v27, v23, v22
	v_mov_b32_e32 v22, v20
	v_mov_b32_e32 v23, v24
	v_and_b32_e32 v8, 0xffff0000, v13
	v_mov_b32_e32 v20, v25
	v_mov_b32_e32 v24, v21
	v_pk_mul_f32 v[18:19], v[22:23], v[18:19]
	v_pk_mul_f32 v[12:13], v[20:21], v[8:9]
	v_pk_mul_f32 v[8:9], v[24:25], v[8:9]
	v_add_f32_e32 v18, v18, v19
	v_sub_f32_e32 v19, v13, v12
	v_add_f32_e32 v20, v8, v9
	v_lshlrev_b32_e32 v9, 16, v10
	v_lshlrev_b32_e32 v8, 16, v14
	v_mov_b32_e32 v12, v4
	v_mov_b32_e32 v13, v0
	v_pk_mul_f32 v[12:13], v[12:13], v[8:9]
	v_sub_f32_e32 v28, v29, v28
	v_sub_f32_e32 v21, v13, v12
	v_mov_b32_e32 v12, v0
	v_mov_b32_e32 v13, v4
	v_pk_mul_f32 v[8:9], v[12:13], v[8:9]
	v_mov_b32_e32 v0, v5
	v_add_f32_e32 v22, v8, v9
	v_and_b32_e32 v9, 0xffff0000, v10
	v_and_b32_e32 v8, 0xffff0000, v14
	v_mov_b32_e32 v4, v1
	v_pk_mul_f32 v[12:13], v[0:1], v[8:9]
	v_pk_mul_f32 v[0:1], v[4:5], v[8:9]
	v_mov_b32_e32 v4, v6
	v_add_f32_e32 v8, v0, v1
	v_lshlrev_b32_e32 v1, 16, v11
	v_lshlrev_b32_e32 v0, 16, v15
	v_mov_b32_e32 v5, v2
	v_pk_mul_f32 v[4:5], v[4:5], v[0:1]
	v_sub_f32_e32 v10, v13, v12
	v_sub_f32_e32 v9, v5, v4
	v_mov_b32_e32 v4, v2
	v_mov_b32_e32 v5, v6
	v_pk_mul_f32 v[0:1], v[4:5], v[0:1]
	v_mov_b32_e32 v2, v7
	v_add_f32_e32 v12, v0, v1
	v_and_b32_e32 v1, 0xffff0000, v11
	v_and_b32_e32 v0, 0xffff0000, v15
	v_mov_b32_e32 v6, v3
	v_pk_mul_f32 v[4:5], v[2:3], v[0:1]
	v_pk_mul_f32 v[0:1], v[6:7], v[0:1]
	v_sub_f32_e32 v2, v5, v4
	v_add_f32_e32 v0, v0, v1
	v_cvt_pk_bf16_f32 v86, v30, v28
	v_cvt_pk_bf16_f32 v87, v27, v19
	v_cvt_pk_bf16_f32 v88, v21, v10
	v_cvt_pk_bf16_f32 v89, v9, v2
	v_cvt_pk_bf16_f32 v82, v31, v26
	v_cvt_pk_bf16_f32 v83, v18, v20
	v_cvt_pk_bf16_f32 v84, v22, v8
	v_cvt_pk_bf16_f32 v85, v12, v0
	v_ashrrev_i32_e32 v12, 3, v16
	v_add_u32_e32 v0, s8, v12
	v_ashrrev_i32_e32 v1, 31, v0
	v_and_b32_e32 v2, 7, v16
	v_lshlrev_b64 v[0:1], 11, v[0:1]
	v_lshlrev_b32_e32 v8, 4, v2
	v_add_u32_e32 v4, s26, v12
	v_mov_b64_e32 v[2:3], s[30:31]
	v_lshl_add_u64 v[0:1], s[28:29], 0, v[0:1]
	v_mov_b32_e32 v9, v65
	v_mad_i64_i32 v[2:3], s[38:39], v4, s77, v[2:3]
	v_lshl_add_u64 v[0:1], v[0:1], 0, v[8:9]
	v_lshl_add_u64 v[2:3], v[2:3], 0, v[8:9]
	s_movk_i32 s38, 0xff
	v_and_b32_e32 v9, 3, v16
	v_cmp_lt_i32_e32 vcc, s38, v16
	s_movk_i32 s38, 0x100
	v_bfe_u32 v13, v16, 2, 6
	v_cmp_gt_i32_e64 s[38:39], s38, v16
	v_lshlrev_b32_e32 v10, 4, v9
.LBB0_1145:
	s_movk_i32 s64, 0xd0
	v_mad_u64_u32 v[134:135], s[64:65], v12, s64, v[8:9]
	v_mul_u32_u24_e32 v11, 0xd0, v13
	v_add_u32_e32 v14, 0, v134
	v_add_u32_e32 v146, v10, v11
	s_waitcnt vmcnt(5)
	ds_write_b128 v14, v[106:109]
	s_and_saveexec_b64 s[64:65], vcc
	s_xor_b64 s[64:65], exec, s[64:65]
	v_add_u32_e32 v146, v10, v11
	s_andn2_saveexec_b64 s[64:65], s[64:65]
	s_cbranch_execz .LBB0_1149
	v_add_u32_e32 v4, 0, v146
	s_waitcnt vmcnt(5)
	ds_write_b128 v4, v[102:105] offset:128
.LBB0_1149:
	s_or_b64 exec, exec, s[64:65]
	s_xor_b64 s[64:65], s[66:67], -1
	s_movk_i32 s67, 0x90
	v_mul_lo_u32 v4, v12, s67
	v_lshlrev_b32_e32 v6, 3, v16
	v_and_b32_e32 v5, 0x60, v8
	v_and_or_b32 v4, v6, 8, v4
	v_add_u32_e32 v148, v4, v5
	v_add_u32_e32 v4, 0, v148
	v_add_u32_e32 v4, 0x3000, v4
	s_lshl_b32 s66, s68, 2
	s_ashr_i32 s68, s69, 7
	s_waitcnt vmcnt(4)
	ds_write2_b64 v4, v[110:111], v[112:113] offset0:128 offset1:130
	v_lshlrev_b32_e32 v2, 4, v16
	s_add_i32 s69, s68, s66
	s_or_b32 s70, s66, 3
	v_mad_i64_i32 v[0:1], s[66:67], v12, s77, 0
	v_and_b32_e32 v2, 0x70, v2
	v_or_b32_e32 v0, v0, v2
	v_lshl_add_u64 v[136:137], s[40:41], 0, v[0:1]
	v_add_u32_e32 v0, s9, v13
	v_ashrrev_i32_e32 v1, 31, v0
	v_lshlrev_b64 v[0:1], 6, v[0:1]
	v_lshl_or_b32 v0, v9, 4, v0
	v_lshl_add_u64 v[138:139], s[96:97], 0, v[0:1]
	v_add_u32_e32 v0, s2, v12
	v_ashrrev_i32_e32 v1, 31, v0
	v_lshlrev_b64 v[0:1], 11, v[0:1]
	v_or_b32_e32 v0, v0, v2
	v_mul_u32_u24_e32 v147, 0xd0, v17
	v_mul_u32_u24_e32 v145, 0x90, v17
	v_add_u32_e32 v149, 0, v64
	v_lshl_add_u64 v[140:141], s[42:43], 0, v[0:1]
	s_mov_b64 s[66:67], 0x100
	v_lshl_add_u64 v[136:137], v[136:137], 0, s[66:67]
	s_mov_b64 s[66:67], 0x2000
	v_lshl_add_u64 v[138:139], v[138:139], 0, s[66:67]
	s_mov_b64 s[66:67], 0x40000
	s_mov_b32 s71, 0
	v_lshl_add_u64 v[140:141], v[140:141], 0, s[66:67]
	v_mov_b32_e32 v16, v65
	v_mov_b32_e32 v17, v65
	v_mov_b32_e32 v18, v65
	v_mov_b32_e32 v19, v65
	v_mov_b32_e32 v20, v65
	v_mov_b32_e32 v21, v65
	v_mov_b32_e32 v22, v65
	v_mov_b32_e32 v23, v65
	v_mov_b32_e32 v24, v65
	v_mov_b32_e32 v25, v65
	v_mov_b32_e32 v26, v65
	v_mov_b32_e32 v27, v65
	v_mov_b32_e32 v28, v65
	v_mov_b32_e32 v29, v65
	v_mov_b32_e32 v30, v65
	v_mov_b32_e32 v31, v65
	v_mov_b32_e32 v0, v65
	v_mov_b32_e32 v1, v65
	v_mov_b32_e32 v2, v65
	v_mov_b32_e32 v3, v65
	v_mov_b32_e32 v4, v65
	v_mov_b32_e32 v5, v65
	v_mov_b32_e32 v6, v65
	v_mov_b32_e32 v7, v65
	v_mov_b32_e32 v8, v65
	v_mov_b32_e32 v9, v65
	v_mov_b32_e32 v10, v65
	v_mov_b32_e32 v11, v65
	v_mov_b32_e32 v12, v65
	v_mov_b32_e32 v13, v65
	v_mov_b32_e32 v14, v65
	v_mov_b32_e32 v15, v65
	v_mov_b32_e32 v144, 0xf149f2ca
	v_mov_b32_e32 v135, 0
	s_waitcnt lgkmcnt(0)
	s_barrier
	s_mov_b32 s72, 0
	s_cmp_lt_u32 s68, 2
	s_cbranch_scc1 .LBB0_1151
	s_barrier
